# P0: issue all 16 x-row loads of a 4-row group up front (one memory latency per group instead of two), gamma in regs
# speedup vs baseline: 1.0126x; 1.0046x over previous
.LBB0_962:
	v_add_u32_e32 v34, s3, v91
	v_ashrrev_i32_e32 v35, 31, v34
	v_lshlrev_b64 v[36:37], 12, v[34:35]
	v_lshl_add_u64 v[36:37], v[96:97], 0, v[36:37]
	global_load_dwordx4 v[78:81], v[36:37], off
	global_load_dwordx4 v[74:77], v[36:37], off offset:16
	global_load_dwordx4 v[70:73], v[36:37], off offset:2048
	global_load_dwordx4 v[66:69], v[36:37], off offset:2064
	v_add_co_u32_e32 v138, vcc, 0x1000, v36
	s_nop 1
	v_addc_co_u32_e32 v139, vcc, 0, v37, vcc
	v_add_co_u32_e32 v140, vcc, 0x3000, v36
	s_nop 1
	v_addc_co_u32_e32 v141, vcc, 0, v37, vcc
	global_load_dwordx4 v[126:129], v[138:139], off
	global_load_dwordx4 v[130:133], v[138:139], off offset:16
	global_load_dwordx4 v[86:89], v[138:139], off offset:2048
	global_load_dwordx4 v[82:85], v[138:139], off offset:2064
	global_load_dwordx4 v[208:211], v[140:141], off offset:-4096
	global_load_dwordx4 v[212:215], v[140:141], off offset:-4080
	global_load_dwordx4 v[216:219], v[140:141], off offset:-2048
	global_load_dwordx4 v[220:223], v[140:141], off offset:-2032
	global_load_dwordx4 v[224:227], v[140:141], off
	global_load_dwordx4 v[228:231], v[140:141], off offset:16
	global_load_dwordx4 v[232:235], v[140:141], off offset:2048
	global_load_dwordx4 v[236:239], v[140:141], off offset:2064
	v_and_b32_e32 v0, 64, v199
	v_xor_b32_e32 v36, 32, v199
	v_add_u32_e32 v55, 64, v0
	v_xor_b32_e32 v37, 16, v199
	v_cmp_lt_i32_e32 vcc, v36, v55
	v_xor_b32_e32 v38, 8, v199
	v_xor_b32_e32 v52, 4, v199
	v_cndmask_b32_e32 v0, v199, v36, vcc
	v_cmp_lt_i32_e32 vcc, v37, v55
	v_lshlrev_b32_e32 v0, 2, v0
	v_xor_b32_e32 v53, 2, v199
	v_cndmask_b32_e32 v56, v199, v37, vcc
	v_cmp_lt_i32_e32 vcc, v38, v55
	v_lshlrev_b32_e32 v113, 2, v56
	v_add_u32_e32 v104, 1, v34
	v_cndmask_b32_e32 v57, v199, v38, vcc
	v_lshlrev_b32_e32 v114, 2, v57
	v_cmp_lt_i32_e32 vcc, v52, v55
	v_add_u32_e32 v102, 2, v34
	v_ashrrev_i32_e32 v105, 31, v104
	v_ashrrev_i32_e32 v103, 31, v102
	v_add_u32_e32 v100, 3, v34
	v_lshlrev_b64 v[34:35], 11, v[34:35]
	v_lshl_add_u64 v[134:135], v[98:99], 0, v[34:35]
	v_xor_b32_e32 v54, 1, v199
	s_mov_b32 s12, 0x800000
	v_ashrrev_i32_e32 v101, 31, v100
	s_waitcnt vmcnt(15)
	v_mov_b32_e32 v38, v79
	s_waitcnt vmcnt(14)
	v_mov_b32_e32 v39, v75
	v_mov_b32_e32 v36, v78
	v_mov_b32_e32 v37, v74
	s_waitcnt vmcnt(13)
	v_mov_b32_e32 v46, v71
	s_waitcnt vmcnt(12)
	v_mov_b32_e32 v47, v67
	v_pk_mul_f32 v[38:39], v[38:39], v[38:39]
	v_mov_b32_e32 v40, v80
	v_mov_b32_e32 v41, v76
	v_mov_b32_e32 v44, v70
	v_mov_b32_e32 v45, v66
	v_pk_mul_f32 v[46:47], v[46:47], v[46:47]
	v_pk_fma_f32 v[36:37], v[36:37], v[36:37], v[38:39]
	v_mov_b32_e32 v42, v81
	v_mov_b32_e32 v43, v77
	v_mov_b32_e32 v48, v72
	v_mov_b32_e32 v49, v68
	v_pk_fma_f32 v[38:39], v[44:45], v[44:45], v[46:47]
	v_pk_fma_f32 v[36:37], v[40:41], v[40:41], v[36:37]
	v_mov_b32_e32 v50, v73
	v_mov_b32_e32 v51, v69
	v_pk_fma_f32 v[38:39], v[48:49], v[48:49], v[38:39]
	v_pk_fma_f32 v[36:37], v[42:43], v[42:43], v[36:37]
	v_pk_fma_f32 v[38:39], v[50:51], v[50:51], v[38:39]
	v_add_f32_e32 v36, v36, v37
	v_add_f32_e32 v36, v36, v38
	v_add_f32_e32 v36, v36, v39
	ds_bpermute_b32 v37, v0, v36
	v_cndmask_b32_e32 v42, v199, v52, vcc
	v_cmp_lt_i32_e32 vcc, v53, v55
	v_lshlrev_b32_e32 v116, 2, v42
	v_lshlrev_b64 v[38:39], 12, v[102:103]
	s_waitcnt lgkmcnt(0)
	v_add_f32_e32 v40, v36, v37
	ds_bpermute_b32 v41, v113, v40
	v_cndmask_b32_e32 v43, v199, v53, vcc
	v_lshlrev_b32_e32 v115, 2, v43
	v_lshlrev_b64 v[36:37], 12, v[104:105]
	v_lshl_add_u64 v[34:35], v[96:97], 0, v[36:37]
	s_waitcnt lgkmcnt(0)
	v_add_f32_e32 v45, v40, v41
	ds_bpermute_b32 v46, v114, v45
	v_lshl_add_u64 v[36:37], v[96:97], 0, v[38:39]
	v_cmp_lt_i32_e32 vcc, v54, v55
	v_cndmask_b32_e32 v44, v199, v54, vcc
	s_waitcnt lgkmcnt(0)
	v_add_f32_e32 v42, v45, v46
	ds_bpermute_b32 v43, v116, v42
	v_lshlrev_b32_e32 v117, 2, v44
	v_lshlrev_b64 v[40:41], 12, v[100:101]
	v_lshl_add_u64 v[136:137], v[96:97], 0, v[40:41]
	s_waitcnt vmcnt(7)
	v_mov_b64_e32 v[62:63], v[208:209]
	v_mov_b64_e32 v[64:65], v[210:211]
	s_waitcnt vmcnt(6)
	v_mov_b64_e32 v[58:59], v[212:213]
	v_mov_b64_e32 v[60:61], v[214:215]
	s_waitcnt vmcnt(5)
	v_mov_b64_e32 v[54:55], v[216:217]
	v_mov_b64_e32 v[56:57], v[218:219]
	s_waitcnt vmcnt(4)
	v_mov_b64_e32 v[50:51], v[220:221]
	v_mov_b64_e32 v[52:53], v[222:223]
	s_waitcnt lgkmcnt(0)
	v_add_f32_e32 v38, v42, v43
	ds_bpermute_b32 v39, v115, v38
	s_waitcnt lgkmcnt(0)
	v_add_f32_e32 v34, v38, v39
	ds_bpermute_b32 v35, v117, v34
	s_waitcnt lgkmcnt(0)
	v_add_f32_e32 v34, v34, v35
	v_fmamk_f32 v34, v34, 0x3a800000, v198
	v_mul_f32_e32 v35, 0x4b800000, v34
	v_cmp_gt_f32_e32 vcc, s12, v34
	s_nop 1
	v_cndmask_b32_e32 v34, v34, v35, vcc
	v_rsq_f32_e32 v138, v34
	s_waitcnt vmcnt(3)
	v_mov_b64_e32 v[46:47], v[224:225]
	v_mov_b64_e32 v[48:49], v[226:227]
	s_waitcnt vmcnt(2)
	v_mov_b64_e32 v[42:43], v[228:229]
	v_mov_b64_e32 v[44:45], v[230:231]
	s_waitcnt vmcnt(1)
	v_mov_b64_e32 v[38:39], v[232:233]
	v_mov_b64_e32 v[40:41], v[234:235]
	s_waitcnt vmcnt(0)
	v_mov_b64_e32 v[34:35], v[236:237]
	v_mov_b64_e32 v[36:37], v[238:239]
	v_mul_f32_e32 v136, 0x45800000, v138
	v_cndmask_b32_e32 v136, v138, v136, vcc
	v_pk_mul_f32 v[74:75], v[74:75], v[136:137] op_sel_hi:[1,0]
	v_pk_mul_f32 v[76:77], v[76:77], v[136:137] op_sel_hi:[1,0]
	v_pk_mul_f32 v[78:79], v[78:79], v[136:137] op_sel_hi:[1,0]
	v_pk_mul_f32 v[80:81], v[80:81], v[136:137] op_sel_hi:[1,0]
	v_pk_mul_f32 v[120:121], v[166:167], v[76:77]
	v_pk_mul_f32 v[76:77], v[164:165], v[74:75]
	v_pk_mul_f32 v[80:81], v[162:163], v[80:81]
	v_pk_mul_f32 v[78:79], v[160:161], v[78:79]
	v_pk_mul_f32 v[70:71], v[70:71], v[136:137] op_sel_hi:[1,0]
	v_cvt_pk_bf16_f32 v74, v78, v79
	v_cvt_pk_bf16_f32 v75, v80, v81
	v_cvt_pk_bf16_f32 v76, v76, v77
	v_cvt_pk_bf16_f32 v77, v120, v121
	global_store_dwordx4 v[134:135], v[74:77], off
	s_nop 0
	v_pk_mul_f32 v[66:67], v[66:67], v[136:137] op_sel_hi:[1,0]
	v_pk_mul_f32 v[68:69], v[68:69], v[136:137] op_sel_hi:[1,0]
	v_pk_mul_f32 v[72:73], v[72:73], v[136:137] op_sel_hi:[1,0]
	v_mov_b32_e32 v118, v128
	v_mov_b32_e32 v119, v132
	v_mov_b32_e32 v120, v88
	v_mov_b32_e32 v121, v84
	v_mov_b32_e32 v122, v129
	v_mov_b32_e32 v123, v133
	v_mov_b32_e32 v124, v89
	v_mov_b32_e32 v125, v85
	v_pk_mul_f32 v[70:71], v[168:169], v[70:71]
	v_pk_mul_f32 v[74:75], v[174:175], v[68:69]
	v_pk_mul_f32 v[68:69], v[172:173], v[66:67]
	v_pk_mul_f32 v[72:73], v[170:171], v[72:73]
	v_cvt_pk_bf16_f32 v66, v70, v71
	v_mov_b32_e32 v76, v127
	v_cvt_pk_bf16_f32 v67, v72, v73
	v_cvt_pk_bf16_f32 v68, v68, v69
	v_cvt_pk_bf16_f32 v69, v74, v75
	global_store_dwordx4 v[134:135], v[66:69], off offset:1024
	s_nop 0
	v_mov_b32_e32 v77, v131
	v_mov_b32_e32 v74, v126
	v_mov_b32_e32 v75, v130
	v_mov_b32_e32 v80, v87
	v_mov_b32_e32 v81, v83
	v_pk_mul_f32 v[76:77], v[76:77], v[76:77]
	v_mov_b32_e32 v78, v86
	v_mov_b32_e32 v79, v82
	v_pk_mul_f32 v[80:81], v[80:81], v[80:81]
	v_pk_fma_f32 v[74:75], v[74:75], v[74:75], v[76:77]
	v_pk_fma_f32 v[76:77], v[78:79], v[78:79], v[80:81]
	v_pk_fma_f32 v[74:75], v[118:119], v[118:119], v[74:75]
	v_pk_fma_f32 v[76:77], v[120:121], v[120:121], v[76:77]
	v_pk_fma_f32 v[74:75], v[122:123], v[122:123], v[74:75]
	v_pk_fma_f32 v[76:77], v[124:125], v[124:125], v[76:77]
	v_add_f32_e32 v74, v74, v75
	v_add_f32_e32 v74, v74, v76
	v_add_f32_e32 v74, v74, v77
	ds_bpermute_b32 v75, v0, v74
	s_waitcnt lgkmcnt(0)
	v_add_f32_e32 v74, v74, v75
	ds_bpermute_b32 v75, v113, v74
	s_waitcnt lgkmcnt(0)
	v_add_f32_e32 v74, v74, v75
	ds_bpermute_b32 v75, v114, v74
	s_waitcnt lgkmcnt(0)
	v_add_f32_e32 v74, v74, v75
	ds_bpermute_b32 v75, v116, v74
	s_waitcnt lgkmcnt(0)
	v_add_f32_e32 v74, v74, v75
	ds_bpermute_b32 v75, v115, v74
	s_waitcnt lgkmcnt(0)
	v_add_f32_e32 v74, v74, v75
	ds_bpermute_b32 v75, v117, v74
	s_waitcnt lgkmcnt(0)
	v_add_f32_e32 v74, v74, v75
	v_fmamk_f32 v74, v74, 0x3a800000, v198
	v_mul_f32_e32 v75, 0x4b800000, v74
	v_cmp_gt_f32_e32 vcc, s12, v74
	s_nop 1
	v_cndmask_b32_e32 v74, v74, v75, vcc
	v_rsq_f32_e32 v76, v74
	v_lshlrev_b64 v[74:75], 11, v[104:105]
	v_lshl_add_u64 v[74:75], v[98:99], 0, v[74:75]
	v_mul_f32_e32 v77, 0x45800000, v76
	v_cndmask_b32_e32 v76, v76, v77, vcc
	v_pk_mul_f32 v[78:79], v[126:127], v[76:77] op_sel_hi:[1,0]
	v_pk_mul_f32 v[80:81], v[128:129], v[76:77] op_sel_hi:[1,0]
	v_pk_mul_f32 v[104:105], v[130:131], v[76:77] op_sel_hi:[1,0]
	v_pk_mul_f32 v[118:119], v[132:133], v[76:77] op_sel_hi:[1,0]
	v_pk_mul_f32 v[82:83], v[82:83], v[76:77] op_sel_hi:[1,0]
	v_pk_mul_f32 v[68:69], v[162:163], v[80:81]
	v_pk_mul_f32 v[66:67], v[160:161], v[78:79]
	v_pk_mul_f32 v[72:73], v[166:167], v[118:119]
	v_pk_mul_f32 v[70:71], v[164:165], v[104:105]
	v_cvt_pk_bf16_f32 v66, v66, v67
	v_cvt_pk_bf16_f32 v67, v68, v69
	v_pk_mul_f32 v[78:79], v[86:87], v[76:77] op_sel_hi:[1,0]
	v_cvt_pk_bf16_f32 v68, v70, v71
	v_cvt_pk_bf16_f32 v69, v72, v73
	global_store_dwordx4 v[74:75], v[66:69], off
	s_nop 0
	v_pk_mul_f32 v[80:81], v[88:89], v[76:77] op_sel_hi:[1,0]
	v_pk_mul_f32 v[76:77], v[84:85], v[76:77] op_sel_hi:[1,0]
	v_mov_b32_e32 v84, v65
	v_mov_b32_e32 v85, v61
	v_mov_b32_e32 v86, v56
	v_mov_b32_e32 v87, v52
	v_mov_b32_e32 v88, v57
	v_mov_b32_e32 v89, v53
	v_pk_mul_f32 v[68:69], v[170:171], v[80:81]
	v_pk_mul_f32 v[66:67], v[168:169], v[78:79]
	v_pk_mul_f32 v[72:73], v[174:175], v[76:77]
	v_pk_mul_f32 v[70:71], v[172:173], v[82:83]
	v_cvt_pk_bf16_f32 v66, v66, v67
	v_cvt_pk_bf16_f32 v67, v68, v69
	v_mov_b32_e32 v76, v63
	v_cvt_pk_bf16_f32 v68, v70, v71
	v_cvt_pk_bf16_f32 v69, v72, v73
	global_store_dwordx4 v[74:75], v[66:69], off offset:1024
	s_nop 0
	v_mov_b32_e32 v77, v59
	v_mov_b32_e32 v74, v62
	v_mov_b32_e32 v75, v58
	v_mov_b32_e32 v82, v55
	v_mov_b32_e32 v83, v51
	v_pk_mul_f32 v[76:77], v[76:77], v[76:77]
	v_mov_b32_e32 v78, v64
	v_mov_b32_e32 v79, v60
	v_mov_b32_e32 v80, v54
	v_mov_b32_e32 v81, v50
	v_pk_mul_f32 v[82:83], v[82:83], v[82:83]
	v_pk_fma_f32 v[74:75], v[74:75], v[74:75], v[76:77]
	v_pk_fma_f32 v[76:77], v[80:81], v[80:81], v[82:83]
	v_pk_fma_f32 v[74:75], v[78:79], v[78:79], v[74:75]
	v_pk_fma_f32 v[76:77], v[86:87], v[86:87], v[76:77]
	v_pk_fma_f32 v[74:75], v[84:85], v[84:85], v[74:75]
	v_pk_fma_f32 v[76:77], v[88:89], v[88:89], v[76:77]
	v_add_f32_e32 v74, v74, v75
	v_add_f32_e32 v74, v74, v76
	v_add_f32_e32 v74, v74, v77
	ds_bpermute_b32 v75, v0, v74
	s_waitcnt lgkmcnt(0)
	v_add_f32_e32 v74, v74, v75
	ds_bpermute_b32 v75, v113, v74
	s_waitcnt lgkmcnt(0)
	v_add_f32_e32 v74, v74, v75
	ds_bpermute_b32 v75, v114, v74
	s_waitcnt lgkmcnt(0)
	v_add_f32_e32 v74, v74, v75
	ds_bpermute_b32 v75, v116, v74
	s_waitcnt lgkmcnt(0)
	v_add_f32_e32 v74, v74, v75
	ds_bpermute_b32 v75, v115, v74
	s_waitcnt lgkmcnt(0)
	v_add_f32_e32 v74, v74, v75
	ds_bpermute_b32 v75, v117, v74
	s_waitcnt lgkmcnt(0)
	v_add_f32_e32 v74, v74, v75
	v_fmamk_f32 v74, v74, 0x3a800000, v198
	v_mul_f32_e32 v75, 0x4b800000, v74
	v_cmp_gt_f32_e32 vcc, s12, v74
	s_nop 1
	v_cndmask_b32_e32 v74, v74, v75, vcc
	v_rsq_f32_e32 v76, v74
	v_lshlrev_b64 v[74:75], 11, v[102:103]
	v_lshl_add_u64 v[74:75], v[98:99], 0, v[74:75]
	v_mul_f32_e32 v77, 0x45800000, v76
	v_cndmask_b32_e32 v76, v76, v77, vcc
	v_pk_mul_f32 v[62:63], v[62:63], v[76:77] op_sel_hi:[1,0]
	v_pk_mul_f32 v[58:59], v[58:59], v[76:77] op_sel_hi:[1,0]
	v_pk_mul_f32 v[60:61], v[60:61], v[76:77] op_sel_hi:[1,0]
	v_pk_mul_f32 v[64:65], v[64:65], v[76:77] op_sel_hi:[1,0]
	v_pk_mul_f32 v[54:55], v[54:55], v[76:77] op_sel_hi:[1,0]
	v_pk_mul_f32 v[50:51], v[50:51], v[76:77] op_sel_hi:[1,0]
	v_pk_mul_f32 v[52:53], v[52:53], v[76:77] op_sel_hi:[1,0]
	v_pk_mul_f32 v[56:57], v[56:57], v[76:77] op_sel_hi:[1,0]
	v_pk_mul_f32 v[62:63], v[160:161], v[62:63]
	v_pk_mul_f32 v[66:67], v[166:167], v[60:61]
	v_pk_mul_f32 v[60:61], v[164:165], v[58:59]
	v_pk_mul_f32 v[64:65], v[162:163], v[64:65]
	v_cvt_pk_bf16_f32 v58, v62, v63
	v_mov_b32_e32 v68, v39
	v_cvt_pk_bf16_f32 v59, v64, v65
	v_cvt_pk_bf16_f32 v60, v60, v61
	v_cvt_pk_bf16_f32 v61, v66, v67
	global_store_dwordx4 v[74:75], v[58:61], off
	s_nop 0
	v_mov_b32_e32 v69, v35
	v_mov_b32_e32 v66, v38
	v_mov_b32_e32 v67, v34
	v_pk_mul_f32 v[68:69], v[68:69], v[68:69]
	v_mov_b32_e32 v70, v40
	v_mov_b32_e32 v71, v36
	v_mov_b32_e32 v72, v41
	v_mov_b32_e32 v73, v37
	v_pk_mul_f32 v[54:55], v[168:169], v[54:55]
	v_pk_mul_f32 v[58:59], v[174:175], v[52:53]
	v_pk_mul_f32 v[52:53], v[172:173], v[50:51]
	v_pk_mul_f32 v[56:57], v[170:171], v[56:57]
	v_cvt_pk_bf16_f32 v50, v54, v55
	v_mov_b32_e32 v60, v47
	v_cvt_pk_bf16_f32 v51, v56, v57
	v_cvt_pk_bf16_f32 v52, v52, v53
	v_cvt_pk_bf16_f32 v53, v58, v59
	global_store_dwordx4 v[74:75], v[50:53], off offset:1024
	s_nop 0
	v_mov_b32_e32 v61, v43
	v_mov_b32_e32 v58, v46
	v_mov_b32_e32 v59, v42
	v_pk_mul_f32 v[60:61], v[60:61], v[60:61]
	v_mov_b32_e32 v62, v48
	v_mov_b32_e32 v63, v44
	v_pk_fma_f32 v[58:59], v[58:59], v[58:59], v[60:61]
	v_mov_b32_e32 v64, v49
	v_mov_b32_e32 v65, v45
	v_pk_fma_f32 v[60:61], v[66:67], v[66:67], v[68:69]
	v_pk_fma_f32 v[58:59], v[62:63], v[62:63], v[58:59]
	v_pk_fma_f32 v[60:61], v[70:71], v[70:71], v[60:61]
	v_pk_fma_f32 v[58:59], v[64:65], v[64:65], v[58:59]
	v_pk_fma_f32 v[60:61], v[72:73], v[72:73], v[60:61]
	v_add_f32_e32 v58, v58, v59
	v_add_f32_e32 v58, v58, v60
	v_add_f32_e32 v58, v58, v61
	ds_bpermute_b32 v0, v0, v58
	s_waitcnt lgkmcnt(0)
	v_add_f32_e32 v0, v58, v0
	ds_bpermute_b32 v58, v113, v0
	s_waitcnt lgkmcnt(0)
	v_add_f32_e32 v0, v0, v58
	ds_bpermute_b32 v58, v114, v0
	s_waitcnt lgkmcnt(0)
	v_add_f32_e32 v0, v0, v58
	ds_bpermute_b32 v58, v116, v0
	s_waitcnt lgkmcnt(0)
	v_add_f32_e32 v0, v0, v58
	ds_bpermute_b32 v58, v115, v0
	s_waitcnt lgkmcnt(0)
	v_add_f32_e32 v0, v0, v58
	ds_bpermute_b32 v58, v117, v0
	s_waitcnt lgkmcnt(0)
	v_add_f32_e32 v0, v0, v58
	v_fmamk_f32 v0, v0, 0x3a800000, v198
	v_mul_f32_e32 v58, 0x4b800000, v0
	v_cmp_gt_f32_e32 vcc, s12, v0
	s_nop 1
	v_cndmask_b32_e32 v0, v0, v58, vcc
	v_rsq_f32_e32 v0, v0
	v_lshlrev_b64 v[58:59], 11, v[100:101]
	v_lshl_add_u64 v[58:59], v[98:99], 0, v[58:59]
	v_mul_f32_e32 v60, 0x45800000, v0
	v_cndmask_b32_e32 v0, v0, v60, vcc
	v_pk_mul_f32 v[46:47], v[46:47], v[0:1] op_sel_hi:[1,0]
	v_pk_mul_f32 v[42:43], v[42:43], v[0:1] op_sel_hi:[1,0]
	v_pk_mul_f32 v[44:45], v[44:45], v[0:1] op_sel_hi:[1,0]
	v_pk_mul_f32 v[48:49], v[48:49], v[0:1] op_sel_hi:[1,0]
	v_pk_mul_f32 v[38:39], v[38:39], v[0:1] op_sel_hi:[1,0]
	v_pk_mul_f32 v[34:35], v[34:35], v[0:1] op_sel_hi:[1,0]
	v_pk_mul_f32 v[36:37], v[36:37], v[0:1] op_sel_hi:[1,0]
	v_pk_mul_f32 v[40:41], v[40:41], v[0:1] op_sel_hi:[1,0]
	v_pk_mul_f32 v[46:47], v[160:161], v[46:47]
	v_pk_mul_f32 v[50:51], v[166:167], v[44:45]
	v_pk_mul_f32 v[44:45], v[164:165], v[42:43]
	v_pk_mul_f32 v[48:49], v[162:163], v[48:49]
	v_cvt_pk_bf16_f32 v42, v46, v47
	s_nop 0
	v_cvt_pk_bf16_f32 v43, v48, v49
	v_cvt_pk_bf16_f32 v44, v44, v45
	v_cvt_pk_bf16_f32 v45, v50, v51
	global_store_dwordx4 v[58:59], v[42:45], off
	s_nop 0
	v_pk_mul_f32 v[38:39], v[168:169], v[38:39]
	v_pk_mul_f32 v[42:43], v[174:175], v[36:37]
	v_pk_mul_f32 v[36:37], v[172:173], v[34:35]
	v_pk_mul_f32 v[40:41], v[170:171], v[40:41]
	v_cvt_pk_bf16_f32 v34, v38, v39
	s_nop 0
	v_cvt_pk_bf16_f32 v35, v40, v41
	v_cvt_pk_bf16_f32 v36, v36, v37
	v_cvt_pk_bf16_f32 v37, v42, v43
	global_store_dwordx4 v[58:59], v[34:37], off offset:1024
	s_or_b64 exec, exec, s[14:15]
	s_andn2_b64 vcc, exec, s[6:7]
	s_cbranch_vccnz .LBB0_955
	s_branch .LBB0_1000
